# P1 prenorm rows interleaved across the 64 waves of a batch (each batch read as one moving 256-KB window instead of 64 separate 128-KB streams)
# baseline (speedup 1.0000x reference)
; DI void prenorm_rows(const float* X, const float* gvec, const float* ada, int sh_off, int sc_off, bf16* U, int row_lo, int row_hi, int gw, int ngw, int lane) {
;     const int nrows = row_hi - row_lo, rpw = (nrows + ngw - 1) / ngw; const int m0 = row_lo + gw * rpw; int m1 = m0 + rpw; if (m1 > row_hi) m1 = row_hi;
;     int curb = -1; f32x4 mul[4], add[4], nx[4];
;     if (m0 < m1) {
; #pragma unroll
;         for (int j = 0; j < 4; ++j) nx[j] = *(const f32x4*)(X + (size_t)m0 * 1024 + 4 * lane + 256 * j);
;     }
;     for (int m = m0; m < m1; ++m) {
.LBB0_83:
	s_abs_i32 s0, s10
	v_cvt_f32_u32_e32 v0, s0
	s_sub_i32 s3, 0, s0
	s_add_i32 s1, s10, 0xffff
	s_xor_b32 s2, s1, s10
	v_rcp_iflag_f32_e32 v0, v0
	s_abs_i32 s1, s1
	s_ashr_i32 s2, s2, 31
	v_mbcnt_lo_u32_b32 v70, -1, 0
	v_mul_f32_e32 v0, 0x4f7ffffe, v0
	v_cvt_u32_f32_e32 v0, v0
	s_nop 0
	v_readfirstlane_b32 s5, v0
	s_mul_i32 s3, s3, s5
	s_mul_hi_u32 s3, s5, s3
	s_add_i32 s5, s5, s3
	s_mul_hi_u32 s3, s1, s5
	s_mul_i32 s5, s3, s0
	s_sub_i32 s1, s1, s5
	s_add_i32 s6, s3, 1
	s_sub_i32 s5, s1, s0
	s_cmp_ge_u32 s1, s0
	s_cselect_b32 s3, s6, s3
	s_cselect_b32 s1, s5, s1
	s_add_i32 s5, s3, 1
	s_cmp_ge_u32 s1, s0
	s_cselect_b32 s0, s5, s3
	s_xor_b32 s0, s0, s2
	s_sub_i32 s0, s0, s2
	s_mul_i32 s6, s0, s4
	s_lshr_b32 s98, s4, 6
	s_lshl_b32 s98, s98, 11
	s_and_b32 s6, s4, 63
	s_or_b32 s6, s6, s98
	s_add_i32 s0, s6, s0
	s_min_i32 s8, s0, 0x10000
	s_cmp_ge_i32 s6, s8
	s_cbranch_scc1 .LBB0_90
	s_ashr_i32 s7, s6, 31
	s_lshl_b64 s[0:1], s[6:7], 12
	s_add_u32 s0, s52, s0
	s_addc_u32 s1, s53, s1
	v_lshlrev_b32_e32 v18, 4, v16
	global_load_dwordx4 v[12:15], v18, s[0:1]
	global_load_dwordx4 v[8:11], v18, s[0:1] offset:1024
	global_load_dwordx4 v[4:7], v18, s[0:1] offset:2048
	global_load_dwordx4 v[0:3], v18, s[0:1] offset:3072
	v_mbcnt_hi_u32_b32 v17, -1, v70
	v_and_b32_e32 v21, 64, v17
	v_add_u32_e32 v21, 64, v21
	v_xor_b32_e32 v22, 1, v17
	v_cmp_lt_i32_e32 vcc, v22, v21
	s_lshl_b64 s[2:3], s[6:7], 11
	v_readlane_b32 s12, v251, 8
	v_cndmask_b32_e32 v22, v17, v22, vcc
	v_lshlrev_b32_e32 v71, 2, v22
	v_xor_b32_e32 v22, 2, v17
	v_cmp_lt_i32_e32 vcc, v22, v21
	v_mov_b32_e32 v19, 0
	v_readlane_b32 s13, v251, 9
	v_cndmask_b32_e32 v22, v17, v22, vcc
	v_lshlrev_b32_e32 v72, 2, v22
	v_xor_b32_e32 v22, 4, v17
	v_cmp_lt_i32_e32 vcc, v22, v21
	s_add_u32 s2, s12, s2
	v_lshlrev_b32_e32 v20, 2, v16
	v_cndmask_b32_e32 v22, v17, v22, vcc
	v_lshlrev_b32_e32 v73, 2, v22
	v_xor_b32_e32 v22, 8, v17
	v_cmp_lt_i32_e32 vcc, v22, v21
	v_lshlrev_b32_e32 v16, 3, v16
	s_addc_u32 s3, s13, s3
	v_cndmask_b32_e32 v22, v17, v22, vcc
	v_lshlrev_b32_e32 v74, 2, v22
	v_xor_b32_e32 v22, 16, v17
	v_cmp_lt_i32_e32 vcc, v22, v21
	v_or_b32_e32 v24, 0x200, v20
	v_or_b32_e32 v26, 0x300, v20
	v_cndmask_b32_e32 v22, v17, v22, vcc
	v_lshlrev_b32_e32 v75, 2, v22
	v_xor_b32_e32 v22, 32, v17
	v_cmp_lt_i32_e32 vcc, v22, v21
	s_mov_b32 s9, -1
	v_lshl_add_u64 v[64:65], s[60:61], 0, v[18:19]
	v_cndmask_b32_e32 v17, v17, v22, vcc
	v_lshlrev_b32_e32 v76, 2, v17
	v_mov_b32_e32 v17, v19
	v_lshl_add_u64 v[16:17], s[2:3], 0, v[16:17]
	s_mov_b64 s[2:3], 0x3000000
	v_or_b32_e32 v22, 0x100, v20
	v_lshl_add_u64 v[66:67], v[16:17], 0, s[2:3]
	v_lshl_add_u64 v[16:17], s[0:1], 0, v[18:19]
	s_mov_b64 s[0:1], 0x40000
	v_lshl_add_u64 v[68:69], v[16:17], 0, s[0:1]
	v_lshlrev_b32_e32 v77, 2, v20
	v_lshlrev_b32_e32 v78, 2, v22
	v_lshlrev_b32_e32 v79, 2, v24
	v_lshlrev_b32_e32 v80, 2, v26
	v_mov_b32_e32 v81, 0x358637bd
	s_mov_b32 s7, 0x800000
	s_mov_b64 s[2:3], 0x20000
	v_readlane_b32 s14, v251, 10
	v_readlane_b32 s15, v251, 11
	s_branch .LBB0_86
